# static s_setprio 1 for waves 4-7 at every phase entry (strategy: one static priority raise for the younger half)
# speedup vs baseline: 1.0068x; 1.0068x over previous
; __global__ void __launch_bounds__(NTHREADS) fwd_kernel(Params p, int ph0, int ph1) {
;     ...
;   const int widx = __builtin_amdgcn_readfirstlane((int)(threadIdx.x >> 6));
;   unsigned nbar = 0;
;   for (int pi = ph0; pi < ph1; ++pi) {
;     int ph = pi, rep = 0;
;     if (N_PROBE > 0 && pi >= N_PHASES) { ph = (pi == N_PHASES) ? PROBE_A : PROBE_B; rep = 1; }
;     int tid;
;     asm volatile("v_mbcnt_lo_u32_b32 %0, -1, 0\n\tv_mbcnt_hi_u32_b32 %0, -1, %0\n\tv_lshl_add_u32 %0, %1, 6, %0" : "=&v"(tid) : "s"(widx));
;     int bid_ = blockIdx.x, nb_ = gridDim.x;
;     asm volatile("" : "+s"(bid_), "+s"(nb_));
;     run_phase(p, ph, tid, rep, bid_, nb_);
.LBB0_19:
	v_readlane_b32 s0, v254, 32
	v_readlane_b32 s1, v254, 33
	v_mbcnt_lo_u32_b32 v239, -1, 0
	v_mbcnt_hi_u32_b32 v239, -1, v239
	v_lshl_add_u32 v239, s34, 6, v239
	s_setprio 0
	s_cmp_lt_u32 s34, 4
	s_cbranch_scc1 .Lprio_done
	s_setprio 1
.Lprio_done:
	s_load_dword s47, s[0:1], 0x0
	s_mov_b32 s45, s25
	s_waitcnt vmcnt(0)
	v_ashrrev_i32_e32 v164, 6, v239
	s_mov_b64 s[0:1], -1
	s_waitcnt lgkmcnt(0)
	v_writelane_b32 v255, s47, 9
	s_lshl_b32 s84, s47, 3
	v_lshl_add_u32 v178, s45, 3, v164
	s_cmp_lg_u32 s48, 20
	s_cbranch_scc1 .LBB0_20
	s_getpc_b64 s[98:99]
